# early per-register reload also in the out-projection GEMM loop
# speedup vs baseline: 1.0672x; 1.0118x over previous
; template <bool VT>
; DI void gemm_mainloop(f32x4 (&acc)[8][4], const char* abase, const char* bbase, unsigned toff, u16* sA, u16* sB, int loff, int wm, int wn, int fr, int fq) {
;     ...
;     __syncthreads();
; #pragma unroll
;     for (int i = 0; i < 8; ++i) *(u32x4*)(sA + loff + i * 32 * GSTR) = ra[i];
; #pragma unroll
;     for (int i = 0; i < 4; ++i) *(u32x4*)(sB + loff + i * 32 * GSTR) = rb[i];
;     __syncthreads();
;     if (kt + 1 < 16) {
;       const int ko = (kt + 1) * 128;
; #pragma unroll
;       for (int i = 0; i < 8; ++i) ra[i] = __builtin_amdgcn_raw_buffer_load_b128(ra_rs, (int)toff, i * 65536 + ko, 0);
; #pragma unroll
;       for (int i = 0; i < 4; ++i) rb[i] = __builtin_amdgcn_raw_buffer_load_b128(rb_rs, (int)toff, i * 65536 + ko, 0);
;     }
.LBB0_397:
	s_cmp_eq_u32 s5, 0x70800
	s_barrier
	s_cbranch_scc1 .Lw_last_o
	s_add_i32 s17, s5, 0xfff90000
	s_add_i32 s18, s5, 0xfffa0000
	s_add_i32 s19, s5, 0xfffb0000
	s_add_i32 s36, s5, 0xfffc0000
	s_add_i32 s37, s5, 0xfffd0000
	s_add_i32 s98, s5, 0xfffe0000
	s_add_i32 s99, s5, 0xffff0000
	s_waitcnt vmcnt(11)
	ds_write_b128 v180, v[66:69]
	buffer_load_dwordx4 v[66:69], v0, s[64:67], s17 offen
	s_waitcnt vmcnt(11)
	ds_write_b128 v180, v[70:73] offset:10240
	buffer_load_dwordx4 v[70:73], v0, s[64:67], s19 offen
	s_waitcnt vmcnt(11)
	ds_write_b128 v180, v[86:89] offset:25600
	buffer_load_dwordx4 v[86:89], v0, s[64:67], s98 offen
	s_waitcnt vmcnt(11)
	ds_write_b128 v180, v[74:77] offset:5120
	buffer_load_dwordx4 v[74:77], v0, s[64:67], s18 offen
	s_waitcnt vmcnt(11)
	ds_write_b128 v180, v[78:81] offset:15360
	buffer_load_dwordx4 v[78:81], v0, s[64:67], s36 offen
	s_waitcnt vmcnt(11)
	ds_write_b128 v180, v[90:93] offset:30720
	buffer_load_dwordx4 v[90:93], v0, s[64:67], s99 offen
	s_waitcnt vmcnt(11)
	ds_write_b128 v180, v[82:85] offset:20480
	buffer_load_dwordx4 v[82:85], v0, s[64:67], s37 offen
	s_waitcnt vmcnt(11)
	ds_write_b128 v180, v[94:97] offset:35840
	buffer_load_dwordx4 v[94:97], v0, s[64:67], s5 offen
	s_waitcnt vmcnt(11)
	ds_write_b128 v180, v[98:101] offset:40960
	buffer_load_dwordx4 v[98:101], v0, s[84:87], s17 offen
	s_waitcnt vmcnt(11)
	ds_write_b128 v180, v[102:105] offset:51200
	buffer_load_dwordx4 v[102:105], v0, s[84:87], s19 offen
	s_waitcnt vmcnt(11)
	ds_write_b128 v180, v[106:109] offset:46080
	buffer_load_dwordx4 v[106:109], v0, s[84:87], s18 offen
	s_waitcnt vmcnt(11)
	ds_write_b128 v180, v[110:113] offset:56320
	buffer_load_dwordx4 v[110:113], v0, s[84:87], s36 offen
	s_waitcnt lgkmcnt(0)
	s_barrier
	s_branch .LBB0_396
.Lw_last_o:
	s_waitcnt vmcnt(11)
	ds_write_b128 v180, v[66:69]
	s_waitcnt vmcnt(10)
	ds_write_b128 v180, v[70:73] offset:10240
	s_waitcnt vmcnt(9)
	ds_write_b128 v180, v[86:89] offset:25600
	s_waitcnt vmcnt(8)
	ds_write_b128 v180, v[74:77] offset:5120
	s_waitcnt vmcnt(7)
	ds_write_b128 v180, v[78:81] offset:15360
	s_waitcnt vmcnt(6)
	ds_write_b128 v180, v[90:93] offset:30720
	s_waitcnt vmcnt(5)
	ds_write_b128 v180, v[82:85] offset:20480
	s_waitcnt vmcnt(4)
	ds_write_b128 v180, v[94:97] offset:35840
	s_waitcnt vmcnt(3)
	ds_write_b128 v180, v[98:101] offset:40960
	s_waitcnt vmcnt(2)
	ds_write_b128 v180, v[102:105] offset:51200
	s_waitcnt vmcnt(1)
	ds_write_b128 v180, v[106:109] offset:46080
	s_waitcnt vmcnt(0)
	ds_write_b128 v180, v[110:113] offset:56320
	s_waitcnt lgkmcnt(0)
	s_barrier
	s_branch .LBB0_396
